# all-edits kernel plus row-pointer constant adds in the w_in projection-tile epilogue
# baseline (speedup 1.0000x reference)
.LBB0_296:
	v_lshl_or_b32 v140, s29, 8, v149
	s_lshl_b32 s29, s60, 2
	s_add_i32 s67, s67, s29
	v_lshl_add_u32 v135, v146, 2, s67
	ds_read_b32 v137, v135
	v_ashrrev_i32_e32 v141, 31, v140
	v_mov_b64_e32 v[138:139], s[0:1]
	s_movk_i32 s29, 0x2400
	v_mad_i64_i32 v[154:155], s[34:35], v136, s29, v[138:139]
	v_lshlrev_b64 v[140:141], 1, v[140:141]
	v_lshl_add_u64 v[154:155], v[154:155], 0, v[140:141]
	s_waitcnt lgkmcnt(0)
	v_mul_f32_e32 v126, v126, v137
	v_mul_f32_e32 v127, v127, v137
	v_mul_f32_e32 v153, v124, v137
	v_mul_f32_e32 v125, v125, v137
	v_mul_f32_e32 v124, v122, v137
	v_cvt_pk_bf16_f32 v122, v126, v127
	v_mul_f32_e32 v128, v128, v137
	v_mul_f32_e32 v129, v129, v137
	v_mul_f32_e32 v156, v123, v137
	v_cvt_pk_bf16_f32 v123, v128, v129
	v_cvt_pk_bf16_f32 v124, v124, v156
	v_cvt_pk_bf16_f32 v125, v153, v125
	global_store_dwordx4 v[154:155], v[122:125], off
	v_mul_f32_e32 v120, v120, v137
	v_mul_f32_e32 v121, v121, v137
	v_mul_f32_e32 v122, v116, v137
	v_mul_f32_e32 v116, v114, v137
	v_mul_f32_e32 v118, v118, v137
	v_mul_f32_e32 v119, v119, v137
	v_mul_f32_e32 v117, v117, v137
	v_mul_f32_e32 v123, v115, v137
	v_cvt_pk_bf16_f32 v114, v118, v119
	v_cvt_pk_bf16_f32 v115, v120, v121
	v_cvt_pk_bf16_f32 v116, v116, v123
	v_cvt_pk_bf16_f32 v117, v122, v117
	global_store_dwordx4 v[154:155], v[114:117], off offset:256
	ds_read_b32 v116, v135 offset:64
	s_waitcnt lgkmcnt(0)
	v_mul_f32_e32 v110, v110, v116
	v_add_co_u32_e32 v114, vcc, 0x24000, v154
	s_nop 1
	v_addc_co_u32_e32 v115, vcc, 0, v155, vcc
	v_mul_f32_e32 v111, v111, v116
	v_mul_f32_e32 v117, v108, v116
	v_mul_f32_e32 v109, v109, v116
	v_mul_f32_e32 v108, v106, v116
	v_cvt_pk_bf16_f32 v106, v110, v111
	v_mul_f32_e32 v112, v112, v116
	v_mul_f32_e32 v113, v113, v116
	v_mul_f32_e32 v118, v107, v116
	v_cvt_pk_bf16_f32 v107, v112, v113
	v_cvt_pk_bf16_f32 v108, v108, v118
	v_cvt_pk_bf16_f32 v109, v117, v109
	global_store_dwordx4 v[114:115], v[106:109], off
	v_mul_f32_e32 v104, v104, v116
	v_mul_f32_e32 v105, v105, v116
	v_mul_f32_e32 v106, v100, v116
	v_mul_f32_e32 v100, v98, v116
	v_mul_f32_e32 v102, v102, v116
	v_mul_f32_e32 v103, v103, v116
	v_mul_f32_e32 v101, v101, v116
	v_mul_f32_e32 v107, v99, v116
	v_cvt_pk_bf16_f32 v98, v102, v103
	v_cvt_pk_bf16_f32 v99, v104, v105
	v_cvt_pk_bf16_f32 v100, v100, v107
	v_cvt_pk_bf16_f32 v101, v106, v101
	global_store_dwordx4 v[114:115], v[98:101], off offset:256
	ds_read_b32 v100, v135 offset:128
	s_waitcnt lgkmcnt(0)
	v_mul_f32_e32 v94, v94, v100
	v_add_co_u32_e32 v98, vcc, 0x48000, v154
	s_nop 1
	v_addc_co_u32_e32 v99, vcc, 0, v155, vcc
	v_mul_f32_e32 v95, v95, v100
	v_mul_f32_e32 v101, v92, v100
	v_mul_f32_e32 v93, v93, v100
	v_mul_f32_e32 v92, v90, v100
	v_cvt_pk_bf16_f32 v90, v94, v95
	v_mul_f32_e32 v96, v96, v100
	v_mul_f32_e32 v97, v97, v100
	v_mul_f32_e32 v102, v91, v100
	v_cvt_pk_bf16_f32 v91, v96, v97
	v_cvt_pk_bf16_f32 v92, v92, v102
	v_cvt_pk_bf16_f32 v93, v101, v93
	global_store_dwordx4 v[98:99], v[90:93], off
	v_mul_f32_e32 v88, v88, v100
	v_mul_f32_e32 v89, v89, v100
	v_mul_f32_e32 v90, v84, v100
	v_mul_f32_e32 v84, v82, v100
	v_mul_f32_e32 v86, v86, v100
	v_mul_f32_e32 v87, v87, v100
	v_mul_f32_e32 v85, v85, v100
	v_mul_f32_e32 v91, v83, v100
	v_cvt_pk_bf16_f32 v82, v86, v87
	v_cvt_pk_bf16_f32 v83, v88, v89
	v_cvt_pk_bf16_f32 v84, v84, v91
	v_cvt_pk_bf16_f32 v85, v90, v85
	global_store_dwordx4 v[98:99], v[82:85], off offset:256
	ds_read_b32 v84, v135 offset:192
	s_waitcnt lgkmcnt(0)
	v_mul_f32_e32 v78, v78, v84
	v_add_co_u32_e32 v82, vcc, 0x6c000, v154
	s_nop 1
	v_addc_co_u32_e32 v83, vcc, 0, v155, vcc
	v_mul_f32_e32 v79, v79, v84
	v_mul_f32_e32 v85, v76, v84
	v_mul_f32_e32 v77, v77, v84
	v_mul_f32_e32 v76, v74, v84
	v_cvt_pk_bf16_f32 v74, v78, v79
	v_mul_f32_e32 v80, v80, v84
	v_mul_f32_e32 v81, v81, v84
	v_mul_f32_e32 v86, v75, v84
	v_cvt_pk_bf16_f32 v75, v80, v81
	v_cvt_pk_bf16_f32 v76, v76, v86
	v_cvt_pk_bf16_f32 v77, v85, v77
	global_store_dwordx4 v[82:83], v[74:77], off
	v_mul_f32_e32 v72, v72, v84
	v_mul_f32_e32 v73, v73, v84
	v_mul_f32_e32 v74, v68, v84
	v_mul_f32_e32 v68, v66, v84
	v_mul_f32_e32 v70, v70, v84
	v_mul_f32_e32 v71, v71, v84
	v_mul_f32_e32 v69, v69, v84
	v_mul_f32_e32 v75, v67, v84
	v_cvt_pk_bf16_f32 v66, v70, v71
	v_cvt_pk_bf16_f32 v67, v72, v73
	v_cvt_pk_bf16_f32 v68, v68, v75
	v_cvt_pk_bf16_f32 v69, v74, v69
	global_store_dwordx4 v[82:83], v[66:69], off offset:256
	ds_read_b32 v68, v135 offset:512
	s_waitcnt lgkmcnt(0)
	v_mul_f32_e32 v62, v62, v68
	v_add_co_u32_e32 v66, vcc, 0x120000, v154
	s_nop 1
	v_addc_co_u32_e32 v67, vcc, 0, v155, vcc
	v_mul_f32_e32 v63, v63, v68
	v_mul_f32_e32 v69, v60, v68
	v_mul_f32_e32 v61, v61, v68
	v_mul_f32_e32 v60, v58, v68
	v_cvt_pk_bf16_f32 v58, v62, v63
	v_mul_f32_e32 v64, v64, v68
	v_mul_f32_e32 v65, v65, v68
	v_mul_f32_e32 v70, v59, v68
	v_cvt_pk_bf16_f32 v59, v64, v65
	v_cvt_pk_bf16_f32 v60, v60, v70
	v_cvt_pk_bf16_f32 v61, v69, v61
	global_store_dwordx4 v[66:67], v[58:61], off
	v_mul_f32_e32 v56, v56, v68
	v_mul_f32_e32 v57, v57, v68
	v_mul_f32_e32 v58, v52, v68
	v_mul_f32_e32 v52, v50, v68
	v_mul_f32_e32 v54, v54, v68
	v_mul_f32_e32 v55, v55, v68
	v_mul_f32_e32 v53, v53, v68
	v_mul_f32_e32 v59, v51, v68
	v_cvt_pk_bf16_f32 v50, v54, v55
	v_cvt_pk_bf16_f32 v51, v56, v57
	v_cvt_pk_bf16_f32 v52, v52, v59
	v_cvt_pk_bf16_f32 v53, v58, v53
	global_store_dwordx4 v[66:67], v[50:53], off offset:256
	ds_read_b32 v52, v135 offset:576
	s_waitcnt lgkmcnt(0)
	v_mul_f32_e32 v46, v46, v52
	v_add_co_u32_e32 v50, vcc, 0x144000, v154
	s_nop 1
	v_addc_co_u32_e32 v51, vcc, 0, v155, vcc
	v_mul_f32_e32 v47, v47, v52
	v_mul_f32_e32 v53, v44, v52
	v_mul_f32_e32 v45, v45, v52
	v_mul_f32_e32 v44, v42, v52
	v_cvt_pk_bf16_f32 v42, v46, v47
	v_mul_f32_e32 v48, v48, v52
	v_mul_f32_e32 v49, v49, v52
	v_mul_f32_e32 v54, v43, v52
	v_cvt_pk_bf16_f32 v43, v48, v49
	v_cvt_pk_bf16_f32 v44, v44, v54
	v_cvt_pk_bf16_f32 v45, v53, v45
	global_store_dwordx4 v[50:51], v[42:45], off
	v_mul_f32_e32 v40, v40, v52
	v_mul_f32_e32 v41, v41, v52
	v_mul_f32_e32 v42, v36, v52
	v_mul_f32_e32 v36, v34, v52
	v_mul_f32_e32 v38, v38, v52
	v_mul_f32_e32 v39, v39, v52
	v_mul_f32_e32 v37, v37, v52
	v_mul_f32_e32 v43, v35, v52
	v_cvt_pk_bf16_f32 v34, v38, v39
	v_cvt_pk_bf16_f32 v35, v40, v41
	v_cvt_pk_bf16_f32 v36, v36, v43
	v_cvt_pk_bf16_f32 v37, v42, v37
	global_store_dwordx4 v[50:51], v[34:37], off offset:256
	ds_read_b32 v36, v135 offset:640
	s_waitcnt lgkmcnt(0)
	v_mul_f32_e32 v30, v30, v36
	v_add_co_u32_e32 v34, vcc, 0x168000, v154
	s_nop 1
	v_addc_co_u32_e32 v35, vcc, 0, v155, vcc
	v_mul_f32_e32 v31, v31, v36
	v_mul_f32_e32 v37, v28, v36
	v_mul_f32_e32 v29, v29, v36
	v_mul_f32_e32 v28, v26, v36
	v_cvt_pk_bf16_f32 v26, v30, v31
	v_mul_f32_e32 v32, v32, v36
	v_mul_f32_e32 v33, v33, v36
	v_mul_f32_e32 v38, v27, v36
	v_cvt_pk_bf16_f32 v27, v32, v33
	v_cvt_pk_bf16_f32 v28, v28, v38
	v_cvt_pk_bf16_f32 v29, v37, v29
	global_store_dwordx4 v[34:35], v[26:29], off
	v_mul_f32_e32 v24, v24, v36
	v_mul_f32_e32 v25, v25, v36
	v_mul_f32_e32 v26, v20, v36
	v_mul_f32_e32 v20, v18, v36
	v_mul_f32_e32 v22, v22, v36
	v_mul_f32_e32 v23, v23, v36
	v_mul_f32_e32 v21, v21, v36
	v_mul_f32_e32 v27, v19, v36
	v_cvt_pk_bf16_f32 v18, v22, v23
	v_cvt_pk_bf16_f32 v19, v24, v25
	v_cvt_pk_bf16_f32 v20, v20, v27
	v_cvt_pk_bf16_f32 v21, v26, v21
	global_store_dwordx4 v[34:35], v[18:21], off offset:256
	ds_read_b32 v20, v135 offset:704
	s_waitcnt lgkmcnt(0)
	v_mul_f32_e32 v14, v14, v20
	v_add_co_u32_e32 v18, vcc, 0x18c000, v154
	s_nop 1
	v_addc_co_u32_e32 v19, vcc, 0, v155, vcc
	v_mul_f32_e32 v15, v15, v20
	v_mul_f32_e32 v21, v12, v20
	v_mul_f32_e32 v13, v13, v20
	v_mul_f32_e32 v12, v10, v20
	v_cvt_pk_bf16_f32 v10, v14, v15
	v_mul_f32_e32 v16, v16, v20
	v_mul_f32_e32 v17, v17, v20
	v_mul_f32_e32 v22, v11, v20
	v_cvt_pk_bf16_f32 v11, v16, v17
	v_cvt_pk_bf16_f32 v12, v12, v22
	v_cvt_pk_bf16_f32 v13, v21, v13
	global_store_dwordx4 v[18:19], v[10:13], off
	v_mul_f32_e32 v5, v5, v20
	v_mul_f32_e32 v8, v8, v20
	v_mul_f32_e32 v10, v4, v20
	v_mul_f32_e32 v4, v2, v20
	v_mul_f32_e32 v9, v9, v20
	v_mul_f32_e32 v6, v6, v20
	v_mul_f32_e32 v7, v7, v20
	v_mul_f32_e32 v11, v3, v20
	v_cvt_pk_bf16_f32 v2, v6, v7
	v_cvt_pk_bf16_f32 v3, v8, v9
	v_cvt_pk_bf16_f32 v4, v4, v11
	v_cvt_pk_bf16_f32 v5, v10, v5
	global_store_dwordx4 v[18:19], v[2:5], off offset:256
	s_andn2_b64 vcc, exec, s[30:31]
	s_mov_b64 s[30:31], -1
	s_cbranch_vccnz .LBB0_278
